# cost-weighted VALU spacing (asm guide 7.5): the in-place softmax exps and row-sum adds spread evenly (weights exp 5/3, add 1) over all QK MFMA gaps instead of packed 4 cost units per gap into the firs
# speedup vs baseline: 1.0002x; 1.0002x over previous
; __device__ __forceinline__ void finishSM(f32x16& p0, f32x16& p1, float alpha, float& l_reg, bf16x8& pa0, bf16x8& pa1, bf16x8& pa2, bf16x8& pa3) {
; #pragma unroll
;   for (int r = 0; r < 16; ++r) p1[r] = __builtin_amdgcn_exp2f(p1[r]);
;   float ps = 0;
; #pragma unroll
;   for (int r = 0; r < 16; ++r) ps += p0[r];
; #pragma unroll
;   for (int r = 0; r < 16; ++r) ps += p1[r];
;   { auto rr = __builtin_amdgcn_permlane32_swap(__float_as_uint(ps), __float_as_uint(ps), false, false);
; __device__ __forceinline__ void qkt(f32x16& p0, f32x16& p1, const char* Kn, const char* Kr, const char* Qr, const bf16x8* qr, const f32x16& negm, int lane) {
;   const int kn = (int)(uintptr_t)Kn + (lane & 31) * 16 + (lane >> 5) * 1024, kr = (int)(uintptr_t)Kr + (lane & 31) * 16 + (lane >> 5) * 1024, qa = (int)(uintptr_t)Qr + lane * 16;
;   bf16x8 a0, a1, b0, b1, qa_, qb_;
;     ...
;   a0 = dsr128<0 * 2048>(kn); a1 = dsr128<0 * 2048 + 512>(kn);
;   b0 = dsr128<1 * 2048>(kn); b1 = dsr128<1 * 2048 + 512>(kn); LGKM_W2(2, a0, a1);
;   p0 = __builtin_amdgcn_mfma_f32_32x32x16_bf16(a0, qr[0], negm, 0, 0, 0); p1 = __builtin_amdgcn_mfma_f32_32x32x16_bf16(a1, qr[0], negm, 0, 0, 0);
;   a0 = dsr128<2 * 2048>(kn); a1 = dsr128<2 * 2048 + 512>(kn); LGKM_W2(2, b0, b1); MM(b0, b1, qr[1]);
;   b0 = dsr128<3 * 2048>(kn); b1 = dsr128<3 * 2048 + 512>(kn); LGKM_W2(2, a0, a1); MM(a0, a1, qr[2]);
;   a0 = dsr128<4 * 2048>(kn); a1 = dsr128<4 * 2048 + 512>(kn); LGKM_W2(2, b0, b1); MM(b0, b1, qr[3]);
;   b0 = dsr128<5 * 2048>(kn); b1 = dsr128<5 * 2048 + 512>(kn); LGKM_W2(2, a0, a1); MM(a0, a1, qr[4]);
;   a0 = dsr128<6 * 2048>(kn); a1 = dsr128<6 * 2048 + 512>(kn); LGKM_W2(2, b0, b1); MM(b0, b1, qr[5]);
;   b0 = dsr128<7 * 2048>(kn); b1 = dsr128<7 * 2048 + 512>(kn); LGKM_W2(2, a0, a1); MM(a0, a1, qr[6]);
;   a0 = dsr128<0 * 2048>(kr); a1 = dsr128<0 * 2048 + 512>(kr); qa_ = dsr128<0 * 1024>(qa); LGKM_W2(3, b0, b1); MM(b0, b1, qr[7]);
;   b0 = dsr128<1 * 2048>(kr); b1 = dsr128<1 * 2048 + 512>(kr); qb_ = dsr128<1 * 1024>(qa); LGKM_W3(3, a0, a1, qa_); MM(a0, a1, qa_);
;   a0 = dsr128<2 * 2048>(kr); a1 = dsr128<2 * 2048 + 512>(kr); qa_ = dsr128<2 * 1024>(qa); LGKM_W3(3, b0, b1, qb_); MM(b0, b1, qb_);
;   b0 = dsr128<3 * 2048>(kr); b1 = dsr128<3 * 2048 + 512>(kr); qb_ = dsr128<3 * 1024>(qa); LGKM_W3(3, a0, a1, qa_); MM(a0, a1, qa_);
;   LGKM_W3(0, b0, b1, qb_); MM(b0, b1, qb_);
;     ...
; }
.LBB0_558:
	ds_read_b128 v[98:101], v204 offset:0
	ds_read_b128 v[178:181], v204 offset:0x200
	ds_read_b128 v[210:213], v204 offset:0x800
	ds_read_b128 v[214:217], v204 offset:0xa00
	v_exp_f32_e32 v82, v82
	s_waitcnt lgkmcnt(2)
	v_exp_f32_e32 v83, v83
	v_mfma_f32_32x32x16_bf16 v[114:129], v[98:101], v[130:133], v[66:81]
	v_exp_f32_e32 v84, v84
	v_exp_f32_e32 v85, v85
	v_exp_f32_e32 v86, v86
	v_exp_f32_e32 v87, v87
	v_exp_f32_e32 v88, v88
	v_exp_f32_e32 v89, v89
	v_mfma_f32_32x32x16_bf16 v[98:113], v[178:181], v[130:133], v[66:81]
	v_exp_f32_e32 v90, v90
	ds_read_b128 v[178:181], v204 offset:0x1000
	ds_read_b128 v[218:221], v204 offset:0x1200
	s_waitcnt lgkmcnt(2)
	s_nop 0
	v_mfma_f32_32x32x16_bf16 v[114:129], v[210:213], v[134:137], v[114:129]
	v_add_f32_e32 v251, 0, v172
	v_add_f32_e32 v251, v175, v251
	v_add_f32_e32 v251, v173, v251
	ds_read_b128 v[210:213], v204 offset:0x1800
	v_mfma_f32_32x32x16_bf16 v[98:113], v[214:217], v[134:137], v[98:113]
	v_add_f32_e32 v251, v176, v251
	ds_read_b128 v[214:217], v204 offset:0x1a00
	s_waitcnt lgkmcnt(2)
	s_nop 0
	v_mfma_f32_32x32x16_bf16 v[114:129], v[178:181], v[138:141], v[114:129]
	v_exp_f32_e32 v91, v91
	v_add_f32_e32 v251, v174, v251
	v_add_f32_e32 v251, v177, v251
	ds_read_b128 v[178:181], v204 offset:0x2000
	v_mfma_f32_32x32x16_bf16 v[98:113], v[218:221], v[138:141], v[98:113]
	v_add_f32_e32 v251, v170, v251
	v_add_f32_e32 v251, v171, v251
	ds_read_b128 v[218:221], v204 offset:0x2200
	s_waitcnt lgkmcnt(2)
	s_nop 0
	v_mfma_f32_32x32x16_bf16 v[114:129], v[210:213], v[142:145], v[114:129]
	v_exp_f32_e32 v92, v92
	v_add_f32_e32 v251, v166, v251
	ds_read_b128 v[210:213], v204 offset:0x2800
	v_mfma_f32_32x32x16_bf16 v[98:113], v[214:217], v[142:145], v[98:113]
	v_add_f32_e32 v251, v168, v251
	v_add_f32_e32 v251, v167, v251
	ds_read_b128 v[214:217], v204 offset:0x2a00
	s_waitcnt lgkmcnt(2)
	s_nop 0
	v_mfma_f32_32x32x16_bf16 v[114:129], v[178:181], v[146:149], v[114:129]
	v_add_f32_e32 v251, v169, v251
	v_exp_f32_e32 v93, v93
	ds_read_b128 v[178:181], v204 offset:0x3000
	v_mfma_f32_32x32x16_bf16 v[98:113], v[218:221], v[146:149], v[98:113]
	v_add_f32_e32 v251, v162, v251
	v_add_f32_e32 v251, v164, v251
	ds_read_b128 v[218:221], v204 offset:0x3200
	s_waitcnt lgkmcnt(2)
	s_nop 0
	v_mfma_f32_32x32x16_bf16 v[114:129], v[210:213], v[150:153], v[114:129]
	v_add_f32_e32 v251, v163, v251
	v_add_f32_e32 v251, v165, v251
	ds_read_b128 v[210:213], v204 offset:0x3800
	v_mfma_f32_32x32x16_bf16 v[98:113], v[214:217], v[150:153], v[98:113]
	v_exp_f32_e32 v94, v94
	v_add_f32_e32 v251, v82, v251
	ds_read_b128 v[214:217], v204 offset:0x3a00
	s_waitcnt lgkmcnt(2)
	s_nop 0
	v_mfma_f32_32x32x16_bf16 v[114:129], v[178:181], v[154:157], v[114:129]
	v_add_f32_e32 v251, v83, v251
	v_add_f32_e32 v251, v84, v251
	v_add_f32_e32 v251, v85, v251
	ds_read_b128 v[178:181], v205 offset:0
	v_mfma_f32_32x32x16_bf16 v[98:113], v[218:221], v[154:157], v[98:113]
	v_exp_f32_e32 v95, v95
	v_add_f32_e32 v251, v86, v251
	ds_read_b128 v[218:221], v205 offset:0x200
	ds_read_b128 v[222:225], v189 offset:0
	s_waitcnt lgkmcnt(3)
	s_nop 0
	v_mfma_f32_32x32x16_bf16 v[114:129], v[210:213], v[158:161], v[114:129]
	v_add_f32_e32 v251, v87, v251
	v_add_f32_e32 v251, v88, v251
	ds_read_b128 v[210:213], v205 offset:0x800
	v_mfma_f32_32x32x16_bf16 v[98:113], v[214:217], v[158:161], v[98:113]
	v_add_f32_e32 v251, v89, v251
	v_exp_f32_e32 v96, v96
	ds_read_b128 v[214:217], v205 offset:0xa00
	ds_read_b128 v[226:229], v189 offset:0x400
	s_waitcnt lgkmcnt(3)
	s_nop 0
	v_mfma_f32_32x32x16_bf16 v[114:129], v[178:181], v[222:225], v[114:129]
	v_add_f32_e32 v251, v90, v251
	v_add_f32_e32 v251, v91, v251
	ds_read_b128 v[178:181], v205 offset:0x1000
	v_mfma_f32_32x32x16_bf16 v[98:113], v[218:221], v[222:225], v[98:113]
	v_add_f32_e32 v251, v92, v251
	v_add_f32_e32 v251, v93, v251
	ds_read_b128 v[218:221], v205 offset:0x1200
	ds_read_b128 v[222:225], v189 offset:0x800
	s_waitcnt lgkmcnt(3)
	s_nop 0
	v_mfma_f32_32x32x16_bf16 v[114:129], v[210:213], v[226:229], v[114:129]
	v_exp_f32_e32 v97, v97
	v_add_f32_e32 v251, v94, v251
	ds_read_b128 v[210:213], v205 offset:0x1800
	v_mfma_f32_32x32x16_bf16 v[98:113], v[214:217], v[226:229], v[98:113]
	v_add_f32_e32 v251, v95, v251
	v_add_f32_e32 v251, v96, v251
	v_add_f32_e32 v251, v97, v251
	ds_read_b128 v[214:217], v205 offset:0x1a00
	ds_read_b128 v[226:229], v189 offset:0xc00
	s_waitcnt lgkmcnt(3)
	s_nop 0
	s_waitcnt lgkmcnt(0)
; #define PV_WAIT(n, f) asm volatile("s_waitcnt lgkmcnt(" #n ")" : "+v"(f.l0), "+v"(f.h0), "+v"(f.l1), "+v"(f.h1), "+v"(f.l2), "+v"(f.h2), "+v"(f.l3), "+v"(f.h3) :: "memory")
; template <bool START>
; __device__ __forceinline__ void partialSM(f32x16& p0, f32x16& p1, float& mhat, f32x16& negm, float& alpha) {
;   float pmax = p0[0];
; #pragma unroll
;   for (int r = 1; r < 16; ++r) pmax = fmaxf(pmax, p0[r]);
; #pragma unroll
;   for (int r = 0; r < 16; ++r) pmax = fmaxf(pmax, p1[r]);
;   { auto rr = __builtin_amdgcn_permlane32_swap(__float_as_uint(pmax), __float_as_uint(pmax), false, false);
;     pmax = fmaxf(__uint_as_float(rr[0]), __uint_as_float(rr[1])); }
;   alpha = 1.f;
;   if (START || __builtin_expect(__any(pmax > THRL), 0)) {
;     const float dl = START ? pmax : fmaxf(pmax, 0.f);
;     mhat += dl;
; #pragma unroll
;     for (int r = 0; r < 16; ++r) { p0[r] -= dl; p1[r] -= dl; }
; #pragma unroll
;     for (int r = 0; r < 16; ++r) negm[r] = -mhat;
;     asm volatile("" : "+v"(negm));
;     if (!START) alpha = __builtin_amdgcn_exp2f(-dl);
;   }
; #pragma unroll
;   for (int r = 0; r < 16; ++r) p0[r] = __builtin_amdgcn_exp2f(p0[r]);
; }
; __device__ __forceinline__ void finishSM(f32x16& p0, f32x16& p1, float alpha, float& l_reg, bf16x8& pa0, bf16x8& pa1, bf16x8& pa2, bf16x8& pa3) {
; #pragma unroll
;   for (int r = 0; r < 16; ++r) p1[r] = __builtin_amdgcn_exp2f(p1[r]);
;   float ps = 0;
; #pragma unroll
;   for (int r = 0; r < 16; ++r) ps += p0[r];
; #pragma unroll
;   for (int r = 0; r < 16; ++r) ps += p1[r];
;   { auto rr = __builtin_amdgcn_permlane32_swap(__float_as_uint(ps), __float_as_uint(ps), false, false);
;     ps = __uint_as_float(rr[0]) + __uint_as_float(rr[1]); }
;   l_reg = l_reg * alpha + ps;
;     ...
;   PK4(p0, 0, pa0); PK4(p0, 8, pa1); PK4(p1, 0, pa2); PK4(p1, 8, pa3);
; __device__ __forceinline__ void pv_d0(f32x16* o, int vb, bf16x8 pa0, bf16x8 pa1, bf16x8 pa2, bf16x8 pa3) {
;   VF fa, fb;
;   pv_rd<0>(fa, vb);
;   pv_rd<1>(fb, vb); PV_WAIT(8, fa); pv_mm(o[0], fa, pa0, pa1, pa2, pa3);
;   pv_rd<2>(fa, vb); PV_WAIT(8, fb); pv_mm(o[1], fb, pa0, pa1, pa2, pa3);
;   pv_rd<3>(fb, vb); PV_WAIT(8, fa); pv_mm(o[2], fa, pa0, pa1, pa2, pa3);
;   PV_WAIT(0, fb); pv_mm(o[3], fb, pa0, pa1, pa2, pa3);
; }
	v_mfma_f32_32x32x16_bf16 v[114:129], v[178:181], v[222:225], v[114:129]
	v_cvt_pk_bf16_f32 v178, v90, v91
	v_cvt_pk_bf16_f32 v179, v92, v93
	v_cvt_pk_bf16_f32 v180, v94, v95
	v_cvt_pk_bf16_f32 v181, v96, v97
	v_cvt_pk_bf16_f32 v90, v172, v175
	v_cvt_pk_bf16_f32 v91, v173, v176
	v_cvt_pk_bf16_f32 v92, v174, v177
	v_mfma_f32_32x32x16_bf16 v[98:113], v[218:221], v[222:225], v[98:113]
	v_cvt_pk_bf16_f32 v93, v170, v171
	v_cvt_pk_bf16_f32 v94, v166, v168
	v_cvt_pk_bf16_f32 v95, v167, v169
	v_cvt_pk_bf16_f32 v96, v162, v164
	v_cvt_pk_bf16_f32 v97, v163, v165
	v_cvt_pk_bf16_f32 v174, v82, v83
	v_cvt_pk_bf16_f32 v175, v84, v85
	v_mfma_f32_32x32x16_bf16 v[114:129], v[210:213], v[226:229], v[114:129]
	v_cvt_pk_bf16_f32 v176, v86, v87
	v_cvt_pk_bf16_f32 v177, v88, v89
	v_mov_b32_e32 v210, v251
	v_mov_b32_e32 v211, v251
	s_nop 1
	v_permlane32_swap_b32_e32 v210, v211
	v_permlane32_swap_b32_e32 v90, v92
	v_mfma_f32_32x32x16_bf16 v[98:113], v[214:217], v[226:229], v[98:113]
	v_permlane32_swap_b32_e32 v91, v93
	v_permlane32_swap_b32_e32 v94, v96
	v_permlane32_swap_b32_e32 v95, v97
	v_permlane32_swap_b32_e32 v174, v176
	v_permlane32_swap_b32_e32 v175, v177
	v_permlane32_swap_b32_e32 v178, v180
	v_permlane32_swap_b32_e32 v179, v181
	s_sub_i32 s0, s76, 64
	s_ashr_i32 s1, s0, 31
	s_lshl_b64 s[84:85], s[0:1], 10
	v_lshl_add_u64 v[82:83], v[192:193], 0, s[84:85]
	s_add_i32 s84, s76, 0xffffff80
	s_ashr_i32 s85, s84, 31
	s_lshl_b64 vcc, s[0:1], 7
	s_lshl_b64 s[84:85], s[84:85], 10
	s_add_u32 s84, s33, s84
	s_addc_u32 s85, s82, s85
	global_load_dwordx4 v[162:165], v[82:83], off
	global_load_dwordx4 v[166:169], v[82:83], off offset:128
	v_lshl_add_u64 v[82:83], v[190:191], 0, vcc
	v_lshl_add_u64 v[86:87], v[0:1], 1, s[84:85]
	global_load_dwordx4 v[170:173], v[82:83], off
	s_nop 0
	global_load_dwordx4 v[82:85], v[86:87], off
	v_add_co_u32_e32 v86, vcc, s81, v86
	s_nop 1
	v_addc_co_u32_e32 v87, vcc, 0, v87, vcc
	global_load_dwordx4 v[86:89], v[86:87], off
	ds_read_b64_tr_b16 v[212:213], v202 offset:0
	ds_read_b64_tr_b16 v[214:215], v202 offset:0x800
	ds_read_b64_tr_b16 v[216:217], v202 offset:0x1000
	ds_read_b64_tr_b16 v[218:219], v202 offset:0x1800
	ds_read_b64_tr_b16 v[220:221], v202 offset:0x2000
	ds_read_b64_tr_b16 v[222:223], v202 offset:0x2800
	ds_read_b64_tr_b16 v[224:225], v202 offset:0x3000
	ds_read_b64_tr_b16 v[226:227], v202 offset:0x3800
	ds_read_b64_tr_b16 v[228:229], v202 offset:0x200
	ds_read_b64_tr_b16 v[230:231], v202 offset:0xa00
	ds_read_b64_tr_b16 v[232:233], v202 offset:0x1200
	ds_read_b64_tr_b16 v[234:235], v202 offset:0x1a00
	ds_read_b64_tr_b16 v[236:237], v202 offset:0x2200
	ds_read_b64_tr_b16 v[238:239], v202 offset:0x2a00
	ds_read_b64_tr_b16 v[240:241], v202 offset:0x3200
	ds_read_b64_tr_b16 v[242:243], v202 offset:0x3a00
	s_nop 0
	s_waitcnt lgkmcnt(8)
	s_nop 0
	v_mfma_f32_32x32x16_bf16 v[18:33], v[90:93], v[212:215], v[18:33]
	ds_read_b64_tr_b16 v[212:213], v202 offset:0x400
	ds_read_b64_tr_b16 v[214:215], v202 offset:0xc00
	v_mfma_f32_32x32x16_bf16 v[18:33], v[94:97], v[216:219], v[18:33]
	ds_read_b64_tr_b16 v[216:217], v202 offset:0x1400
	ds_read_b64_tr_b16 v[218:219], v202 offset:0x1c00
	v_mfma_f32_32x32x16_bf16 v[18:33], v[174:177], v[220:223], v[18:33]
	ds_read_b64_tr_b16 v[220:221], v202 offset:0x2400
	ds_read_b64_tr_b16 v[222:223], v202 offset:0x2c00
	v_mfma_f32_32x32x16_bf16 v[18:33], v[178:181], v[224:227], v[18:33]
	ds_read_b64_tr_b16 v[224:225], v202 offset:0x3400
	ds_read_b64_tr_b16 v[226:227], v202 offset:0x3c00
	s_waitcnt lgkmcnt(8)
	s_nop 0
	v_mfma_f32_32x32x16_bf16 v[50:65], v[90:93], v[228:231], v[50:65]
	ds_read_b64_tr_b16 v[228:229], v202 offset:0x600
	ds_read_b64_tr_b16 v[230:231], v202 offset:0xe00
	v_mfma_f32_32x32x16_bf16 v[50:65], v[94:97], v[232:235], v[50:65]
	ds_read_b64_tr_b16 v[232:233], v202 offset:0x1600
	ds_read_b64_tr_b16 v[234:235], v202 offset:0x1e00
	v_mfma_f32_32x32x16_bf16 v[50:65], v[174:177], v[236:239], v[50:65]
	ds_read_b64_tr_b16 v[236:237], v202 offset:0x2600
	ds_read_b64_tr_b16 v[238:239], v202 offset:0x2e00
	v_mfma_f32_32x32x16_bf16 v[50:65], v[178:181], v[240:243], v[50:65]
	ds_read_b64_tr_b16 v[240:241], v202 offset:0x3600
	ds_read_b64_tr_b16 v[242:243], v202 offset:0x3e00
	s_waitcnt lgkmcnt(8)
	s_nop 0
	s_waitcnt lgkmcnt(0)
	v_mfma_f32_32x32x16_bf16 v[34:49], v[90:93], v[212:215], v[34:49]
	v_mfma_f32_32x32x16_bf16 v[2:17], v[90:93], v[228:231], v[2:17]
	v_max_f32_e32 v90, v115, v115
	v_max_f32_e32 v91, v114, v114
	v_max_f32_e32 v90, v91, v90
	v_max3_f32 v90, v90, v116, v117
	v_max3_f32 v90, v90, v118, v119
	v_max3_f32 v90, v90, v120, v121
	v_max3_f32 v90, v90, v122, v123
	v_mfma_f32_32x32x16_bf16 v[34:49], v[94:97], v[216:219], v[34:49]
	v_max3_f32 v90, v90, v124, v125
	v_max3_f32 v90, v90, v126, v127
	v_max3_f32 v90, v90, v128, v129
	v_max3_f32 v90, v90, v98, v99
	v_max3_f32 v90, v90, v100, v101
	v_max3_f32 v90, v90, v102, v103
	v_max3_f32 v90, v90, v104, v105
	v_mfma_f32_32x32x16_bf16 v[2:17], v[94:97], v[232:235], v[2:17]
	v_max3_f32 v90, v90, v106, v107
	v_max3_f32 v90, v90, v108, v109
	v_max3_f32 v90, v90, v110, v111
	v_max3_f32 v90, v90, v112, v113
	v_mov_b32_e32 v91, v90
	s_nop 1
	v_permlane32_swap_b32_e32 v90, v91
	v_mfma_f32_32x32x16_bf16 v[34:49], v[174:177], v[220:223], v[34:49]
	v_max_f32_e32 v91, v91, v91
	v_max_f32_e32 v90, v90, v90
	v_max_f32_e32 v90, v90, v91
	v_cmp_lt_f32_e32 vcc, s89, v90
	v_mfma_f32_32x32x16_bf16 v[2:17], v[174:177], v[236:239], v[2:17]
	v_mfma_f32_32x32x16_bf16 v[34:49], v[178:181], v[224:227], v[34:49]
	v_mfma_f32_32x32x16_bf16 v[2:17], v[178:181], v[240:243], v[2:17]
	s_cbranch_vccnz .LBB0_576
	v_mov_b32_e32 v212, 1.0
	s_branch .LBB0_563

; template <bool START>
; __device__ __forceinline__ void partialSM(f32x16& p0, f32x16& p1, float& mhat, f32x16& negm, float& alpha) {
;     ...
;   for (int r = 0; r < 16; ++r) p0[r] = __builtin_amdgcn_exp2f(p0[r]);
; }
; __device__ __forceinline__ void finishSM(f32x16& p0, f32x16& p1, float alpha, float& l_reg, bf16x8& pa0, bf16x8& pa1, bf16x8& pa2, bf16x8& pa3) {
; #pragma unroll
;   for (int r = 0; r < 16; ++r) p1[r] = __builtin_amdgcn_exp2f(p1[r]);
;   float ps = 0;
; #pragma unroll
;   for (int r = 0; r < 16; ++r) ps += p0[r];
; #pragma unroll
;   for (int r = 0; r < 16; ++r) ps += p1[r];
;   { auto rr = __builtin_amdgcn_permlane32_swap(__float_as_uint(ps), __float_as_uint(ps), false, false);
;     ps = __uint_as_float(rr[0]) + __uint_as_float(rr[1]); }
;   l_reg = l_reg * alpha + ps;
; __device__ __forceinline__ void qkt(f32x16& p0, f32x16& p1, const char* Kn, const char* Kr, const char* Qr, const bf16x8* qr, const f32x16& negm, int lane) {
;   const int kn = (int)(uintptr_t)Kn + (lane & 31) * 16 + (lane >> 5) * 1024, kr = (int)(uintptr_t)Kr + (lane & 31) * 16 + (lane >> 5) * 1024, qa = (int)(uintptr_t)Qr + lane * 16;
;   bf16x8 a0, a1, b0, b1, qa_, qb_;
;     ...
;   a0 = dsr128<0 * 2048>(kn); a1 = dsr128<0 * 2048 + 512>(kn);
;   b0 = dsr128<1 * 2048>(kn); b1 = dsr128<1 * 2048 + 512>(kn); LGKM_W2(2, a0, a1);
;   p0 = __builtin_amdgcn_mfma_f32_32x32x16_bf16(a0, qr[0], negm, 0, 0, 0); p1 = __builtin_amdgcn_mfma_f32_32x32x16_bf16(a1, qr[0], negm, 0, 0, 0);
;   a0 = dsr128<2 * 2048>(kn); a1 = dsr128<2 * 2048 + 512>(kn); LGKM_W2(2, b0, b1); MM(b0, b1, qr[1]);
;   b0 = dsr128<3 * 2048>(kn); b1 = dsr128<3 * 2048 + 512>(kn); LGKM_W2(2, a0, a1); MM(a0, a1, qr[2]);
;   a0 = dsr128<4 * 2048>(kn); a1 = dsr128<4 * 2048 + 512>(kn); LGKM_W2(2, b0, b1); MM(b0, b1, qr[3]);
;   b0 = dsr128<5 * 2048>(kn); b1 = dsr128<5 * 2048 + 512>(kn); LGKM_W2(2, a0, a1); MM(a0, a1, qr[4]);
;   a0 = dsr128<6 * 2048>(kn); a1 = dsr128<6 * 2048 + 512>(kn); LGKM_W2(2, b0, b1); MM(b0, b1, qr[5]);
;   b0 = dsr128<7 * 2048>(kn); b1 = dsr128<7 * 2048 + 512>(kn); LGKM_W2(2, a0, a1); MM(a0, a1, qr[6]);
;   a0 = dsr128<0 * 2048>(kr); a1 = dsr128<0 * 2048 + 512>(kr); qa_ = dsr128<0 * 1024>(qa); LGKM_W2(3, b0, b1); MM(b0, b1, qr[7]);
;   b0 = dsr128<1 * 2048>(kr); b1 = dsr128<1 * 2048 + 512>(kr); qb_ = dsr128<1 * 1024>(qa); LGKM_W3(3, a0, a1, qa_); MM(a0, a1, qa_);
.LBB0_563:
	s_lshl_b64 vcc, s[0:1], 9
	v_exp_f32_e32 v230, v114
	v_exp_f32_e32 v231, v115
	v_exp_f32_e32 v232, v116
	v_exp_f32_e32 v233, v117
	v_exp_f32_e32 v234, v118
	v_exp_f32_e32 v235, v119
	s_waitcnt vmcnt(0)
	ds_write_b128 v197, v[162:165] offset:32768
	ds_write_b128 v197, v[166:169] offset:40960
	ds_write_b128 v200, v[170:173]
	ds_write_b128 v198, v[82:85] offset:16384
	ds_write_b128 v199, v[86:89] offset:16384
	v_exp_f32_e32 v236, v120
	v_exp_f32_e32 v237, v121
	v_exp_f32_e32 v238, v122
	v_exp_f32_e32 v239, v123
	v_exp_f32_e32 v240, v124
	v_exp_f32_e32 v241, v125
	v_exp_f32_e32 v242, v126
	v_exp_f32_e32 v243, v127
	v_exp_f32_e32 v244, v128
	v_exp_f32_e32 v245, v129
	s_waitcnt lgkmcnt(0)
	s_barrier
	ds_read_b128 v[82:85], v187 offset:0
	ds_read_b128 v[174:177], v187 offset:0x200
	ds_read_b128 v[178:181], v187 offset:0x800
	ds_read_b128 v[214:217], v187 offset:0xa00
	v_exp_f32_e32 v98, v98
	s_waitcnt lgkmcnt(2)
	v_exp_f32_e32 v99, v99
	v_mfma_f32_32x32x16_bf16 v[114:129], v[82:85], v[130:133], v[66:81]
	v_exp_f32_e32 v100, v100
	v_exp_f32_e32 v101, v101
	v_exp_f32_e32 v102, v102
	v_exp_f32_e32 v103, v103
	v_exp_f32_e32 v104, v104
	v_exp_f32_e32 v105, v105
	v_mfma_f32_32x32x16_bf16 v[82:97], v[174:177], v[130:133], v[66:81]
	v_exp_f32_e32 v106, v106
	ds_read_b128 v[174:177], v187 offset:0x1000
	ds_read_b128 v[218:221], v187 offset:0x1200
	s_waitcnt lgkmcnt(2)
	s_nop 0
	v_mfma_f32_32x32x16_bf16 v[114:129], v[178:181], v[134:137], v[114:129]
	v_add_f32_e32 v251, 0, v230
	v_add_f32_e32 v251, v231, v251
	v_add_f32_e32 v251, v232, v251
	ds_read_b128 v[178:181], v187 offset:0x1800
	v_mfma_f32_32x32x16_bf16 v[82:97], v[214:217], v[134:137], v[82:97]
	v_add_f32_e32 v251, v233, v251
	ds_read_b128 v[214:217], v187 offset:0x1a00
	s_waitcnt lgkmcnt(2)
	s_nop 0
	v_mfma_f32_32x32x16_bf16 v[114:129], v[174:177], v[138:141], v[114:129]
	v_exp_f32_e32 v107, v107
	v_add_f32_e32 v251, v234, v251
	v_add_f32_e32 v251, v235, v251
	ds_read_b128 v[174:177], v187 offset:0x2000
	v_mfma_f32_32x32x16_bf16 v[82:97], v[218:221], v[138:141], v[82:97]
	v_add_f32_e32 v251, v236, v251
	v_add_f32_e32 v251, v237, v251
	ds_read_b128 v[218:221], v187 offset:0x2200
	s_waitcnt lgkmcnt(2)
	s_nop 0
	v_mfma_f32_32x32x16_bf16 v[114:129], v[178:181], v[142:145], v[114:129]
	v_exp_f32_e32 v108, v108
	v_add_f32_e32 v251, v238, v251
	ds_read_b128 v[178:181], v187 offset:0x2800
	v_mfma_f32_32x32x16_bf16 v[82:97], v[214:217], v[142:145], v[82:97]
	v_add_f32_e32 v251, v239, v251
	v_add_f32_e32 v251, v240, v251
	ds_read_b128 v[214:217], v187 offset:0x2a00
	s_waitcnt lgkmcnt(2)
	s_nop 0
	v_mfma_f32_32x32x16_bf16 v[114:129], v[174:177], v[146:149], v[114:129]
	v_add_f32_e32 v251, v241, v251
	v_exp_f32_e32 v109, v109
	ds_read_b128 v[174:177], v187 offset:0x3000
	v_mfma_f32_32x32x16_bf16 v[82:97], v[218:221], v[146:149], v[82:97]
	v_add_f32_e32 v251, v242, v251
	v_add_f32_e32 v251, v243, v251
	ds_read_b128 v[218:221], v187 offset:0x3200
	s_waitcnt lgkmcnt(2)
	s_nop 0
	v_mfma_f32_32x32x16_bf16 v[114:129], v[178:181], v[150:153], v[114:129]
	v_add_f32_e32 v251, v244, v251
	v_add_f32_e32 v251, v245, v251
	ds_read_b128 v[178:181], v187 offset:0x3800
	v_mfma_f32_32x32x16_bf16 v[82:97], v[214:217], v[150:153], v[82:97]
	v_exp_f32_e32 v110, v110
	v_add_f32_e32 v251, v98, v251
	ds_read_b128 v[214:217], v187 offset:0x3a00
	s_waitcnt lgkmcnt(2)
	s_nop 0
	v_mfma_f32_32x32x16_bf16 v[114:129], v[174:177], v[154:157], v[114:129]
	v_add_f32_e32 v251, v99, v251
	v_add_f32_e32 v251, v100, v251
	v_add_f32_e32 v251, v101, v251
	ds_read_b128 v[174:177], v203 offset:0
	v_mfma_f32_32x32x16_bf16 v[82:97], v[218:221], v[154:157], v[82:97]
	v_exp_f32_e32 v111, v111
	v_add_f32_e32 v251, v102, v251
	ds_read_b128 v[218:221], v203 offset:0x200
	ds_read_b128 v[222:225], v189 offset:0
	s_waitcnt lgkmcnt(3)
	s_nop 0
	v_mfma_f32_32x32x16_bf16 v[114:129], v[178:181], v[158:161], v[114:129]
	v_add_f32_e32 v251, v103, v251
	v_add_f32_e32 v251, v104, v251
	ds_read_b128 v[178:181], v203 offset:0x800
	v_mfma_f32_32x32x16_bf16 v[82:97], v[214:217], v[158:161], v[82:97]
	v_add_f32_e32 v251, v105, v251
	v_exp_f32_e32 v112, v112
	ds_read_b128 v[214:217], v203 offset:0xa00
	ds_read_b128 v[226:229], v189 offset:0x400
	s_waitcnt lgkmcnt(3)
	s_nop 0
	v_mfma_f32_32x32x16_bf16 v[114:129], v[174:177], v[222:225], v[114:129]
	v_add_f32_e32 v251, v106, v251
	v_add_f32_e32 v251, v107, v251
	ds_read_b128 v[174:177], v203 offset:0x1000
	v_mfma_f32_32x32x16_bf16 v[82:97], v[218:221], v[222:225], v[82:97]
	v_add_f32_e32 v251, v108, v251
	v_add_f32_e32 v251, v109, v251
	ds_read_b128 v[218:221], v203 offset:0x1200
	ds_read_b128 v[222:225], v189 offset:0x800
	s_waitcnt lgkmcnt(3)
	s_nop 0
	v_mfma_f32_32x32x16_bf16 v[114:129], v[178:181], v[226:229], v[114:129]
	v_exp_f32_e32 v113, v113
	v_add_f32_e32 v251, v110, v251
	ds_read_b128 v[178:181], v203 offset:0x1800
	v_mfma_f32_32x32x16_bf16 v[82:97], v[214:217], v[226:229], v[82:97]
	v_add_f32_e32 v251, v111, v251
	v_add_f32_e32 v251, v112, v251
	v_add_f32_e32 v251, v113, v251
	ds_read_b128 v[214:217], v203 offset:0x1a00
	ds_read_b128 v[226:229], v189 offset:0xc00
	s_waitcnt lgkmcnt(3)
	s_nop 0
	s_waitcnt lgkmcnt(0)
	v_mfma_f32_32x32x16_bf16 v[114:129], v[174:177], v[222:225], v[114:129]
	v_mfma_f32_32x32x16_bf16 v[114:129], v[178:181], v[226:229], v[114:129]
	v_cvt_pk_bf16_f32 v178, v106, v107
	v_cvt_pk_bf16_f32 v179, v108, v109
	v_cvt_pk_bf16_f32 v180, v110, v111
	v_cvt_pk_bf16_f32 v181, v112, v113
	v_cvt_pk_bf16_f32 v106, v230, v231
	v_cvt_pk_bf16_f32 v107, v232, v233
	v_cvt_pk_bf16_f32 v108, v234, v235
	v_mfma_f32_32x32x16_bf16 v[82:97], v[218:221], v[222:225], v[82:97]
	v_cvt_pk_bf16_f32 v109, v236, v237
	v_cvt_pk_bf16_f32 v110, v238, v239
	v_cvt_pk_bf16_f32 v111, v240, v241
	v_cvt_pk_bf16_f32 v112, v242, v243
	v_cvt_pk_bf16_f32 v113, v244, v245
	v_cvt_pk_bf16_f32 v174, v98, v99
	v_cvt_pk_bf16_f32 v175, v100, v101
	v_mfma_f32_32x32x16_bf16 v[82:97], v[214:217], v[226:229], v[82:97]
	v_cvt_pk_bf16_f32 v176, v102, v103
	v_cvt_pk_bf16_f32 v177, v104, v105
	v_mov_b32_e32 v213, v251
	v_mov_b32_e32 v214, v251
	s_nop 1
	v_permlane32_swap_b32_e32 v213, v214
	v_permlane32_swap_b32_e32 v106, v108
	v_permlane32_swap_b32_e32 v107, v109
	v_permlane32_swap_b32_e32 v110, v112
	v_permlane32_swap_b32_e32 v111, v113
	v_permlane32_swap_b32_e32 v174, v176
	v_permlane32_swap_b32_e32 v175, v177
	v_permlane32_swap_b32_e32 v178, v180
	v_permlane32_swap_b32_e32 v179, v181
	s_cmp_lt_u32 s83, s94
	s_cselect_b64 s[0:1], -1, 0
	s_cmp_ge_u32 s83, s94
	s_cbranch_scc1 .LBB0_565
	s_ashr_i32 s77, s76, 31
	s_lshl_b64 s[84:85], s[76:77], 10
	s_lshl_b64 s[86:87], s[76:77], 7
	v_lshl_add_u64 v[98:99], v[192:193], 0, s[84:85]
	global_load_dwordx4 v[162:165], v[98:99], off
	global_load_dwordx4 v[166:169], v[98:99], off offset:128
	v_lshl_add_u64 v[98:99], v[190:191], 0, s[86:87]
	global_load_dwordx4 v[170:173], v[98:99], off

; template <bool START>
; __device__ __forceinline__ void partialSM(f32x16& p0, f32x16& p1, float& mhat, f32x16& negm, float& alpha) {
;     ...
;   for (int r = 0; r < 16; ++r) p0[r] = __builtin_amdgcn_exp2f(p0[r]);
; }
; __device__ __forceinline__ void finishSM(f32x16& p0, f32x16& p1, float alpha, float& l_reg, bf16x8& pa0, bf16x8& pa1, bf16x8& pa2, bf16x8& pa3) {
; #pragma unroll
;   for (int r = 0; r < 16; ++r) p1[r] = __builtin_amdgcn_exp2f(p1[r]);
;   float ps = 0;
; #pragma unroll
;   for (int r = 0; r < 16; ++r) ps += p0[r];
; #pragma unroll
;   for (int r = 0; r < 16; ++r) ps += p1[r];
;   { auto rr = __builtin_amdgcn_permlane32_swap(__float_as_uint(ps), __float_as_uint(ps), false, false);
;     ps = __uint_as_float(rr[0]) + __uint_as_float(rr[1]); }
;   l_reg = l_reg * alpha + ps;
; __device__ __forceinline__ void qkt(f32x16& p0, f32x16& p1, const char* Kn, const char* Kr, const char* Qr, const bf16x8* qr, const f32x16& negm, int lane) {
;   const int kn = (int)(uintptr_t)Kn + (lane & 31) * 16 + (lane >> 5) * 1024, kr = (int)(uintptr_t)Kr + (lane & 31) * 16 + (lane >> 5) * 1024, qa = (int)(uintptr_t)Qr + lane * 16;
;   bf16x8 a0, a1, b0, b1, qa_, qb_;
;     ...
;   a0 = dsr128<0 * 2048>(kn); a1 = dsr128<0 * 2048 + 512>(kn);
;   b0 = dsr128<1 * 2048>(kn); b1 = dsr128<1 * 2048 + 512>(kn); LGKM_W2(2, a0, a1);
;   p0 = __builtin_amdgcn_mfma_f32_32x32x16_bf16(a0, qr[0], negm, 0, 0, 0); p1 = __builtin_amdgcn_mfma_f32_32x32x16_bf16(a1, qr[0], negm, 0, 0, 0);
;   a0 = dsr128<2 * 2048>(kn); a1 = dsr128<2 * 2048 + 512>(kn); LGKM_W2(2, b0, b1); MM(b0, b1, qr[1]);
;   b0 = dsr128<3 * 2048>(kn); b1 = dsr128<3 * 2048 + 512>(kn); LGKM_W2(2, a0, a1); MM(a0, a1, qr[2]);
;   a0 = dsr128<4 * 2048>(kn); a1 = dsr128<4 * 2048 + 512>(kn); LGKM_W2(2, b0, b1); MM(b0, b1, qr[3]);
;   b0 = dsr128<5 * 2048>(kn); b1 = dsr128<5 * 2048 + 512>(kn); LGKM_W2(2, a0, a1); MM(a0, a1, qr[4]);
;   a0 = dsr128<6 * 2048>(kn); a1 = dsr128<6 * 2048 + 512>(kn); LGKM_W2(2, b0, b1); MM(b0, b1, qr[5]);
;   b0 = dsr128<7 * 2048>(kn); b1 = dsr128<7 * 2048 + 512>(kn); LGKM_W2(2, a0, a1); MM(a0, a1, qr[6]);
;   a0 = dsr128<0 * 2048>(kr); a1 = dsr128<0 * 2048 + 512>(kr); qa_ = dsr128<0 * 1024>(qa); LGKM_W2(3, b0, b1); MM(b0, b1, qr[7]);
;   b0 = dsr128<1 * 2048>(kr); b1 = dsr128<1 * 2048 + 512>(kr); qb_ = dsr128<1 * 1024>(qa); LGKM_W3(3, a0, a1, qa_); MM(a0, a1, qa_);
.LBB0_1377:
	v_exp_f32_e32 v234, v114
	v_exp_f32_e32 v235, v115
	v_exp_f32_e32 v236, v116
	v_exp_f32_e32 v237, v117
	v_exp_f32_e32 v238, v118
	v_exp_f32_e32 v239, v119
	s_waitcnt vmcnt(0)
	ds_write_b128 v202, v[162:165] offset:32768
	ds_write_b128 v202, v[166:169] offset:40960
	ds_write_b128 v205, v[170:173]
	ds_write_b128 v203, v[82:85] offset:16384
	ds_write_b128 v204, v[86:89] offset:16384
	v_exp_f32_e32 v240, v120
	v_exp_f32_e32 v241, v121
	v_exp_f32_e32 v242, v122
	v_exp_f32_e32 v243, v123
	v_exp_f32_e32 v244, v124
	v_exp_f32_e32 v245, v125
	v_exp_f32_e32 v246, v126
	v_exp_f32_e32 v247, v127
	v_exp_f32_e32 v248, v128
	v_exp_f32_e32 v249, v129
	s_waitcnt lgkmcnt(0)
	s_barrier
	ds_read_b128 v[82:85], v208 offset:0
	ds_read_b128 v[174:177], v208 offset:0x200
	ds_read_b128 v[178:181], v208 offset:0x800
	ds_read_b128 v[218:221], v208 offset:0xa00
	v_exp_f32_e32 v98, v98
	s_waitcnt lgkmcnt(2)
	v_exp_f32_e32 v99, v99
	v_mfma_f32_32x32x16_bf16 v[114:129], v[82:85], v[130:133], v[66:81]
	v_exp_f32_e32 v100, v100
	v_exp_f32_e32 v101, v101
	v_exp_f32_e32 v102, v102
	v_exp_f32_e32 v103, v103
	v_exp_f32_e32 v104, v104
	v_exp_f32_e32 v105, v105
	v_mfma_f32_32x32x16_bf16 v[82:97], v[174:177], v[130:133], v[66:81]
	v_exp_f32_e32 v106, v106
	ds_read_b128 v[174:177], v208 offset:0x1000
	ds_read_b128 v[222:225], v208 offset:0x1200
	s_waitcnt lgkmcnt(2)
	s_nop 0
	v_mfma_f32_32x32x16_bf16 v[114:129], v[178:181], v[134:137], v[114:129]
	v_add_f32_e32 v251, 0, v234
	v_add_f32_e32 v251, v235, v251
	v_add_f32_e32 v251, v236, v251
	ds_read_b128 v[178:181], v208 offset:0x1800
	v_mfma_f32_32x32x16_bf16 v[82:97], v[218:221], v[134:137], v[82:97]
	v_add_f32_e32 v251, v237, v251
	ds_read_b128 v[218:221], v208 offset:0x1a00
	s_waitcnt lgkmcnt(2)
	s_nop 0
	v_mfma_f32_32x32x16_bf16 v[114:129], v[174:177], v[138:141], v[114:129]
	v_exp_f32_e32 v107, v107
	v_add_f32_e32 v251, v238, v251
	v_add_f32_e32 v251, v239, v251
	ds_read_b128 v[174:177], v208 offset:0x2000
	v_mfma_f32_32x32x16_bf16 v[82:97], v[222:225], v[138:141], v[82:97]
	v_add_f32_e32 v251, v240, v251
	v_add_f32_e32 v251, v241, v251
	ds_read_b128 v[222:225], v208 offset:0x2200
	s_waitcnt lgkmcnt(2)
	s_nop 0
	v_mfma_f32_32x32x16_bf16 v[114:129], v[178:181], v[142:145], v[114:129]
	v_exp_f32_e32 v108, v108
	v_add_f32_e32 v251, v242, v251
	ds_read_b128 v[178:181], v208 offset:0x2800
	v_mfma_f32_32x32x16_bf16 v[82:97], v[218:221], v[142:145], v[82:97]
	v_add_f32_e32 v251, v243, v251
	v_add_f32_e32 v251, v244, v251
	ds_read_b128 v[218:221], v208 offset:0x2a00
	s_waitcnt lgkmcnt(2)
	s_nop 0
	v_mfma_f32_32x32x16_bf16 v[114:129], v[174:177], v[146:149], v[114:129]
	v_add_f32_e32 v251, v245, v251
	v_exp_f32_e32 v109, v109
	ds_read_b128 v[174:177], v208 offset:0x3000
	v_mfma_f32_32x32x16_bf16 v[82:97], v[222:225], v[146:149], v[82:97]
	v_add_f32_e32 v251, v246, v251
	v_add_f32_e32 v251, v247, v251
	ds_read_b128 v[222:225], v208 offset:0x3200
	s_waitcnt lgkmcnt(2)
	s_nop 0
	v_mfma_f32_32x32x16_bf16 v[114:129], v[178:181], v[150:153], v[114:129]
	v_add_f32_e32 v251, v248, v251
	v_add_f32_e32 v251, v249, v251
	ds_read_b128 v[178:181], v208 offset:0x3800
	v_mfma_f32_32x32x16_bf16 v[82:97], v[218:221], v[150:153], v[82:97]
	v_exp_f32_e32 v110, v110
	v_add_f32_e32 v251, v98, v251
	ds_read_b128 v[218:221], v208 offset:0x3a00
	s_waitcnt lgkmcnt(2)
	s_nop 0
	v_mfma_f32_32x32x16_bf16 v[114:129], v[174:177], v[154:157], v[114:129]
	v_add_f32_e32 v251, v99, v251
	v_add_f32_e32 v251, v100, v251
	v_add_f32_e32 v251, v101, v251
	ds_read_b128 v[174:177], v209 offset:0
	v_mfma_f32_32x32x16_bf16 v[82:97], v[222:225], v[154:157], v[82:97]
	v_exp_f32_e32 v111, v111
	v_add_f32_e32 v251, v102, v251
	ds_read_b128 v[222:225], v209 offset:0x200
	ds_read_b128 v[226:229], v201 offset:0
	s_waitcnt lgkmcnt(3)
	s_nop 0
	v_mfma_f32_32x32x16_bf16 v[114:129], v[178:181], v[158:161], v[114:129]
	v_add_f32_e32 v251, v103, v251
	v_add_f32_e32 v251, v104, v251
	ds_read_b128 v[178:181], v209 offset:0x800
	v_mfma_f32_32x32x16_bf16 v[82:97], v[218:221], v[158:161], v[82:97]
	v_add_f32_e32 v251, v105, v251
	v_exp_f32_e32 v112, v112
	ds_read_b128 v[218:221], v209 offset:0xa00
	ds_read_b128 v[230:233], v201 offset:0x400
	s_waitcnt lgkmcnt(3)
	s_nop 0
	v_mfma_f32_32x32x16_bf16 v[114:129], v[174:177], v[226:229], v[114:129]
	v_add_f32_e32 v251, v106, v251
	v_add_f32_e32 v251, v107, v251
	ds_read_b128 v[174:177], v209 offset:0x1000
	v_mfma_f32_32x32x16_bf16 v[82:97], v[222:225], v[226:229], v[82:97]
	v_add_f32_e32 v251, v108, v251
	v_add_f32_e32 v251, v109, v251
	ds_read_b128 v[222:225], v209 offset:0x1200
	ds_read_b128 v[226:229], v201 offset:0x800
	s_waitcnt lgkmcnt(3)
	s_nop 0
	v_mfma_f32_32x32x16_bf16 v[114:129], v[178:181], v[230:233], v[114:129]
	v_exp_f32_e32 v113, v113
	v_add_f32_e32 v251, v110, v251
	ds_read_b128 v[178:181], v209 offset:0x1800
	v_mfma_f32_32x32x16_bf16 v[82:97], v[218:221], v[230:233], v[82:97]
	v_add_f32_e32 v251, v111, v251
	v_add_f32_e32 v251, v112, v251
	v_add_f32_e32 v251, v113, v251
	ds_read_b128 v[218:221], v209 offset:0x1a00
	ds_read_b128 v[230:233], v201 offset:0xc00
	s_waitcnt lgkmcnt(3)
	s_nop 0
	s_waitcnt lgkmcnt(0)
	v_mfma_f32_32x32x16_bf16 v[114:129], v[174:177], v[226:229], v[114:129]
	v_mfma_f32_32x32x16_bf16 v[114:129], v[178:181], v[230:233], v[114:129]
	v_cvt_pk_bf16_f32 v178, v106, v107
	v_cvt_pk_bf16_f32 v179, v108, v109
	v_cvt_pk_bf16_f32 v180, v110, v111
	v_cvt_pk_bf16_f32 v181, v112, v113
	v_cvt_pk_bf16_f32 v106, v234, v235
	v_cvt_pk_bf16_f32 v107, v236, v237
	v_cvt_pk_bf16_f32 v108, v238, v239
	v_mfma_f32_32x32x16_bf16 v[82:97], v[222:225], v[226:229], v[82:97]
	v_cvt_pk_bf16_f32 v109, v240, v241
	v_cvt_pk_bf16_f32 v110, v242, v243
	v_cvt_pk_bf16_f32 v111, v244, v245
	v_cvt_pk_bf16_f32 v112, v246, v247
	v_cvt_pk_bf16_f32 v113, v248, v249
	v_cvt_pk_bf16_f32 v174, v98, v99
	v_cvt_pk_bf16_f32 v175, v100, v101
	v_mfma_f32_32x32x16_bf16 v[82:97], v[218:221], v[230:233], v[82:97]
	v_cvt_pk_bf16_f32 v176, v102, v103
	v_cvt_pk_bf16_f32 v177, v104, v105
	v_mov_b32_e32 v218, v251
	v_mov_b32_e32 v219, v251
	s_nop 1
	v_permlane32_swap_b32_e32 v218, v219
	v_permlane32_swap_b32_e32 v106, v108
	v_permlane32_swap_b32_e32 v107, v109
	v_permlane32_swap_b32_e32 v110, v112
	v_permlane32_swap_b32_e32 v111, v113
	v_permlane32_swap_b32_e32 v174, v176
	v_permlane32_swap_b32_e32 v175, v177
	v_permlane32_swap_b32_e32 v178, v180
	v_permlane32_swap_b32_e32 v179, v181
	s_cmp_lt_u32 s91, s96
	s_cselect_b64 s[0:1], -1, 0
	s_cmp_ge_u32 s91, s96
	s_cbranch_scc1 .LBB0_1379
	v_add_co_u32_e32 v98, vcc, 0x60f0000, v196
	s_nop 1
	v_addc_co_u32_e32 v99, vcc, 0, v197, vcc
	global_load_dwordx4 v[162:165], v[98:99], off
	global_load_dwordx4 v[166:169], v[98:99], off offset:128
	v_add_co_u32_e32 v98, vcc, 0xe1c6000, v194
	s_nop 1
	v_addc_co_u32_e32 v99, vcc, 0, v195, vcc
	global_load_dwordx4 v[170:173], v[98:99], off
